# attention: O stores no longer wait for the abandoned K/V prefetch (the next unit's first-load wait covers it)
# speedup vs baseline: 1.0426x; 1.0032x over previous
.LBB0_648:
	v_mov_b32_e32 v139, v0
	s_waitcnt lgkmcnt(0)
	v_lshl_add_u64 v[216:217], v[138:139], 1, v[156:157]
	v_cvt_pk_bf16_f32 v4, v48, v49
	v_cvt_pk_bf16_f32 v5, v50, v51
	v_cvt_pk_bf16_f32 v6, v52, v53
	v_cvt_pk_bf16_f32 v7, v54, v55
	v_cvt_pk_bf16_f32 v8, v56, v57
	v_cvt_pk_bf16_f32 v9, v58, v59
	v_cvt_pk_bf16_f32 v10, v60, v61
	v_cvt_pk_bf16_f32 v11, v62, v63
	v_cvt_pk_bf16_f32 v12, v64, v65
	v_cvt_pk_bf16_f32 v13, v66, v67
	v_cvt_pk_bf16_f32 v14, v68, v69
	v_cvt_pk_bf16_f32 v15, v70, v71
	v_cvt_pk_bf16_f32 v218, v72, v73
	v_cvt_pk_bf16_f32 v219, v74, v75
	v_cvt_pk_bf16_f32 v220, v76, v77
	v_cvt_pk_bf16_f32 v221, v78, v79
	s_nop 1
	v_permlane32_swap_b32_e32 v4, v6
	v_permlane32_swap_b32_e32 v5, v7
	v_permlane32_swap_b32_e32 v8, v10
	v_permlane32_swap_b32_e32 v9, v11
	v_permlane32_swap_b32_e32 v12, v14
	v_permlane32_swap_b32_e32 v13, v15
	v_permlane32_swap_b32_e32 v218, v220
	v_permlane32_swap_b32_e32 v219, v221
	global_store_dwordx4 v[216:217], v[4:7], off
	global_store_dwordx4 v[216:217], v[8:11], off offset:32
	global_store_dwordx4 v[216:217], v[12:15], off offset:64
	global_store_dwordx4 v[216:217], v[218:221], off offset:96
	s_add_i32 s20, s20, s72
	s_cmpk_lt_i32 s20, 0x4000
	s_cbranch_scc0 .LBB0_656
